# P + P5 attention: next tile's first five K fragments read from LDS before the barrier (during the PV stage) into free registers, so the S MFMAs start right after the barrier
# speedup vs baseline: 1.0063x; 1.0063x over previous
; #define LAS __attribute__((address_space(3)))
;     ...
;     const int rp = w >> 1, kh = w & 1;
;     bf16x8 qf[2][4];
; #pragma unroll
;     for (int rb = 0; rb < 2; ++rb)
; #pragma unroll
;         for (int ks = 0; ks < 4; ++ks) qf[rb][ks] = *(const LAS bf16x8*)(Qs + (32 * rp + 16 * rb + fr) * QP + 32 * ks + 8 * fq);
;     f32x4 o[2][8];
; #pragma unroll
;     for (int rb = 0; rb < 2; ++rb)
; #pragma unroll
;         for (int i = 0; i < 8; ++i) o[rb][i] = (f32x4){0.f, 0.f, 0.f, 0.f};
;     float lrun[2] = {0.f, 0.f};
;     auto compute = [&](int buf, int t) {
;         const LAS bf16* Ks = (const LAS bf16*)(lds + koff(buf)); const LAS bf16* VT = (const LAS bf16*)(lds + voff(buf));
;         bf16x8 kf[2][4]; float bias[2][2][4];
; #pragma unroll
;         for (int kb = 0; kb < 2; ++kb)
; #pragma unroll
;             for (int ks = 0; ks < 4; ++ks) kf[kb][ks] = *(const LAS bf16x8*)(Ks + (32 * kh + 16 * kb + fr) * QP + 32 * ks + 8 * fq);
;         if (MODE == 0) { const LAS float* bp = BT + (2047 - 16 - (q0 + 32 * rp + fr - t * 64 - 32 * kh - 4 * fq));
;     ...
;     if (MODE == 0) {
;         __syncthreads();
;         int cur = 0;
.LBB0_120:
	s_xor_b64 s[74:75], s[40:41], -1
	v_mad_i64_i32 v[2:3], s[40:41], v6, s97, 0
	v_and_b32_e32 v6, 15, v155
	v_ashrrev_i32_e32 v164, 7, v155
	v_lshl_or_b32 v156, v164, 5, v6
	v_and_b32_e32 v165, 48, v155
	v_mul_lo_u32 v4, v156, s94
	v_add3_u32 v4, s92, v165, v4
	s_waitcnt lgkmcnt(0)
	s_barrier
	ds_read_b128 v[76:79], v4
	ds_read_b128 v[80:83], v4 offset:64
	ds_read_b128 v[84:87], v4 offset:128
	ds_read_b128 v[88:91], v4 offset:192
	ds_read_b128 v[92:95], v4 offset:4608
	ds_read_b128 v[96:99], v4 offset:4672
	ds_read_b128 v[100:103], v4 offset:4736
	ds_read_b128 v[104:107], v4 offset:4800
	v_bfe_u32 v166, v155, 6, 1
	v_lshl_or_b32 v4, v166, 5, v6
	v_mul_u32_u24_e32 v167, 0x120, v4
	v_and_b32_e32 v4, 3, v155
	v_lshlrev_b32_e32 v4, 5, v4
	v_mov_b32_e32 v5, v153
	v_lshl_add_u64 v[0:1], v[0:1], 0, v[4:5]
	v_lshl_add_u64 v[158:159], s[44:45], 0, v[0:1]
	v_lshl_add_u64 v[0:1], v[2:3], 0, v[152:153]
	v_lshl_add_u64 v[160:161], s[46:47], 0, v[0:1]
	v_lshl_or_b32 v0, v166, 7, v165
	v_add_lshl_u32 v1, s58, v6, 2
	v_sub_u32_e32 v0, v0, v1
	v_and_b32_e32 v1, 0xffffff80, v155
	v_sub_u32_e32 v0, v0, v1
	s_add_i32 s40, s58, 0x80
	v_add_u32_e32 v170, s1, v0
	v_mov_b32_e32 v0, 0
	s_mov_b32 s77, s25
	s_lshr_b32 s40, s40, 6
	s_mov_b32 s41, 5
	v_lshlrev_b32_e32 v168, 6, v166
	v_mul_u32_u24_e32 v169, 0xa0, v6
	s_mov_b32 s63, 0
	v_mov_b32_e32 v1, v0
	v_mov_b32_e32 v2, v0
	v_mov_b32_e32 v3, v0
	v_mov_b32_e32 v4, v0
	v_mov_b32_e32 v5, v0
	v_mov_b32_e32 v6, v0
	v_mov_b32_e32 v7, v0
	v_mov_b32_e32 v8, v0
	v_mov_b32_e32 v9, v0
	v_mov_b32_e32 v10, v0
	v_mov_b32_e32 v11, v0
	v_mov_b32_e32 v12, v0
	v_mov_b32_e32 v13, v0
	v_mov_b32_e32 v14, v0
	v_mov_b32_e32 v15, v0
	v_mov_b32_e32 v16, v0
	v_mov_b32_e32 v17, v0
	v_mov_b32_e32 v18, v0
	v_mov_b32_e32 v19, v0
	v_mov_b32_e32 v20, v0
	v_mov_b32_e32 v21, v0
	v_mov_b32_e32 v22, v0
	v_mov_b32_e32 v23, v0
	v_mov_b32_e32 v24, v0
	v_mov_b32_e32 v25, v0
	v_mov_b32_e32 v26, v0
	v_mov_b32_e32 v27, v0
	v_mov_b32_e32 v28, v0
	v_mov_b32_e32 v29, v0
	v_mov_b32_e32 v30, v0
	v_mov_b32_e32 v31, v0
	v_mov_b32_e32 v64, v0
	v_mov_b32_e32 v65, v0
	v_mov_b32_e32 v66, v0
	v_mov_b32_e32 v67, v0
	v_mov_b32_e32 v68, v0
	v_mov_b32_e32 v69, v0
	v_mov_b32_e32 v70, v0
	v_mov_b32_e32 v71, v0
	v_mov_b32_e32 v72, v0
	v_mov_b32_e32 v73, v0
	v_mov_b32_e32 v74, v0
	v_mov_b32_e32 v75, v0
	v_mov_b32_e32 v108, v0
	v_mov_b32_e32 v109, v0
	v_mov_b32_e32 v110, v0
	v_mov_b32_e32 v111, v0
	v_mov_b32_e32 v112, v0
	v_mov_b32_e32 v113, v0
	v_mov_b32_e32 v114, v0
	v_mov_b32_e32 v115, v0
	v_mov_b32_e32 v116, v0
	v_mov_b32_e32 v117, v0
	v_mov_b32_e32 v118, v0
	v_mov_b32_e32 v119, v0
	v_mov_b32_e32 v120, v0
	v_mov_b32_e32 v121, v0
	v_mov_b32_e32 v122, v0
	v_mov_b32_e32 v123, v0
	v_mov_b32_e32 v124, v0
	v_mov_b32_e32 v125, v0
	v_mov_b32_e32 v126, v0
	v_mov_b32_e32 v127, v0
	v_mov_b32_e32 v150, v0
	v_mov_b32_e32 v151, v0
	s_waitcnt lgkmcnt(0)
	s_barrier
	s_mul_i32 s69, s63, 0x9800
	v_add3_u32 v239, s69, v165, v167
	ds_read_b128 v[228:231], v239
	ds_read_b128 v[232:235], v239 offset:4608
	ds_read_b128 v[240:243], v239 offset:64
	ds_read_b128 v[244:247], v239 offset:4672
	ds_read_b128 v[248:251], v239 offset:128
	s_branch .LBB0_122
;     ...
;     auto compute = [&](int buf, int t) {
;         const LAS bf16* Ks = (const LAS bf16*)(lds + koff(buf)); const LAS bf16* VT = (const LAS bf16*)(lds + voff(buf));
;         bf16x8 kf[2][4]; float bias[2][2][4];
; #pragma unroll
;         for (int kb = 0; kb < 2; ++kb)
; #pragma unroll
;             for (int ks = 0; ks < 4; ++ks) kf[kb][ks] = *(const LAS bf16x8*)(Ks + (32 * kh + 16 * kb + fr) * QP + 32 * ks + 8 * fq);
;         if (MODE == 0) { const LAS float* bp = BT + (2047 - 16 - (q0 + 32 * rp + fr - t * 64 - 32 * kh - 4 * fq));
; #pragma unroll
;                 for (int kb = 0; kb < 2; ++kb)
; #pragma unroll
;                     for (int i = 0; i < 4; ++i) bias[0][kb][i] = bp[16 * (kb + 1) + i]; }
;         __builtin_amdgcn_sched_barrier(0);
;         f32x4 s[2][2];
; #pragma unroll
;         for (int rb = 0; rb < 2; ++rb)
; #pragma unroll
;             for (int kb = 0; kb < 2; ++kb) s[rb][kb] = (f32x4){0.f, 0.f, 0.f, 0.f};
;         bf16x8 pf[2];
;         auto smax = [&](int rb) {
;             if (MODE == 0) { s[rb][0] = s[rb][0] + (f32x4){bias[rb][0][0], bias[rb][0][1], bias[rb][0][2], bias[rb][0][3]}; s[rb][1] = s[rb][1] + (f32x4){bias[rb][1][0], bias[rb][1][1], bias[rb][1][2], bias[rb][1][3]}; }
;             else { s[rb][0] = s[rb][0] - bref; s[rb][1] = s[rb][1] - bref; }
;             float ps = 0.f;
; #pragma unroll
;             for (int kb = 0; kb < 2; ++kb)
; #pragma unroll
;                 for (int i = 0; i < 4; ++i) { s[rb][kb][i] = __builtin_amdgcn_exp2f(s[rb][kb][i]); ps += s[rb][kb][i]; }
;             lrun[rb] += ps;
;             u32x4 pw; pw.x = pk2(s[rb][0][0], s[rb][0][1]); pw.y = pk2(s[rb][0][2], s[rb][0][3]); pw.z = pk2(s[rb][1][0], s[rb][1][1]); pw.w = pk2(s[rb][1][2], s[rb][1][3]);
;             pf[rb] = __builtin_bit_cast(bf16x8, pw); };
; #pragma unroll
;         for (int ks = 0; ks < 4; ++ks)
; #pragma unroll
;             for (int kb = 0; kb < 2; ++kb) MMA16(kf[kb][ks], qf[0][ks], s[0][kb]);
;         __builtin_amdgcn_sched_barrier(0);
;         bf16x8 vf[8];
; #pragma unroll
;         for (int db = 0; db < 8; ++db) vf[db] = *(const LAS bf16x8*)(VT + (16 * db + fr) * VPA + 32 * kh + 8 * fq);
;         if (MODE == 0) { const LAS float* bp = BT + (2047 - 16 - (q0 + 32 * rp + fr - t * 64 - 32 * kh - 4 * fq));
; #pragma unroll
;             for (int kb = 0; kb < 2; ++kb)
; #pragma unroll
.LBB0_121:
	v_pk_add_f32 v[142:143], v[142:143], 0 op_sel_hi:[1,0]
	s_add_i32 s78, s78, 0x9800
	v_pk_add_f32 v[140:141], v[140:141], v[142:143]
	s_cmp_lt_i32 s63, 2
	v_pk_add_f32 v[138:139], v[138:139], v[140:141]
	s_cselect_b32 s63, s78, 0
	v_pk_add_f32 v[136:137], v[136:137], v[138:139]
	s_add_i32 s63, s63, 0
	v_pk_add_f32 v[134:135], v[134:135], v[136:137]
	v_add_u32_e32 v171, s63, v165
	v_pk_add_f32 v[132:133], v[132:133], v[134:135]
	v_add_u32_e32 v182, v171, v167
	v_pk_add_f32 v[130:131], v[130:131], v[132:133]
	v_pk_add_f32 v[128:129], v[128:129], v[130:131]
	v_pk_add_f32 v[150:151], v[150:151], v[128:129]
	ds_read_b128 v[172:175], v182 offset:192
	ds_read_b128 v[192:195], v182 offset:4736
	ds_read_b128 v[196:199], v182 offset:4800
	ds_read2_b32 v[182:183], v170 offset0:80 offset1:81
	ds_read2_b32 v[184:185], v170 offset0:82 offset1:83
	ds_read2_b32 v[188:189], v170 offset0:96 offset1:97
	ds_read2_b32 v[190:191], v170 offset0:98 offset1:99
	s_waitcnt lgkmcnt(7)
	v_mfma_f32_16x16x32_bf16 v[200:203], v[228:231], v[76:79], 0
	v_mfma_f32_16x16x32_bf16 v[204:207], v[232:235], v[76:79], 0
	v_mfma_f32_16x16x32_bf16 v[200:203], v[240:243], v[80:83], v[200:203]
	v_mfma_f32_16x16x32_bf16 v[204:207], v[244:247], v[80:83], v[204:207]
	v_mfma_f32_16x16x32_bf16 v[200:203], v[248:251], v[84:87], v[200:203]
	s_waitcnt lgkmcnt(5)
	v_mfma_f32_16x16x32_bf16 v[204:207], v[192:195], v[84:87], v[204:207]
	v_mfma_f32_16x16x32_bf16 v[200:203], v[172:175], v[88:91], v[200:203]
	s_waitcnt lgkmcnt(4)
	v_mfma_f32_16x16x32_bf16 v[204:207], v[196:199], v[88:91], v[204:207]
	v_mfma_f32_16x16x32_bf16 v[208:211], v[228:231], v[92:95], 0
	ds_read2_b32 v[212:213], v170 offset0:64 offset1:65
	v_add3_u32 v171, v171, v168, v169
	s_waitcnt lgkmcnt(3)
	s_nop 1
	v_pk_add_f32 v[184:185], v[184:185], v[202:203]
	v_pk_add_f32 v[182:183], v[182:183], v[200:201]
	s_waitcnt lgkmcnt(1)
	v_pk_add_f32 v[190:191], v[190:191], v[206:207]
	v_mfma_f32_16x16x32_bf16 v[136:139], v[232:235], v[92:95], 0
	ds_read_b128 v[128:131], v171 offset:36352
	v_pk_add_f32 v[188:189], v[188:189], v[204:205]
	v_exp_f32_e32 v207, v182
	v_mfma_f32_16x16x32_bf16 v[200:203], v[240:243], v[96:99], v[208:211]
	ds_read_b128 v[132:135], v171 offset:18432
	v_exp_f32_e32 v183, v183
	v_exp_f32_e32 v185, v185
	v_mfma_f32_16x16x32_bf16 v[144:147], v[244:247], v[96:99], v[136:139]
	v_exp_f32_e32 v209, v184
	v_exp_f32_e32 v211, v188
	v_exp_f32_e32 v189, v189
	ds_read_b128 v[136:139], v171 offset:20992
	v_mfma_f32_16x16x32_bf16 v[200:203], v[248:251], v[100:103], v[200:203]
	ds_read_b128 v[140:143], v171 offset:23552
	v_exp_f32_e32 v191, v191
	v_mfma_f32_16x16x32_bf16 v[192:195], v[192:195], v[100:103], v[144:147]
	s_nop 2
	ds_read_b128 v[144:147], v171 offset:26112
	v_mfma_f32_16x16x32_bf16 v[192:195], v[196:199], v[104:107], v[192:195]
	v_mfma_f32_16x16x32_bf16 v[172:175], v[172:175], v[104:107], v[200:203]
	ds_read2_b32 v[196:197], v170 offset0:66 offset1:67
	s_waitcnt lgkmcnt(0)
	s_nop 5
	v_pk_add_f32 v[174:175], v[196:197], v[174:175]
	ds_read_b128 v[196:199], v171 offset:33792
	v_exp_f32_e32 v208, v174
	v_exp_f32_e32 v184, v175
	ds_read2_b32 v[174:175], v170 offset0:82 offset1:83
	s_waitcnt lgkmcnt(0)
	v_pk_add_f32 v[174:175], v[174:175], v[194:195]
	ds_read2_b32 v[204:205], v170 offset0:80 offset1:81
	s_waitcnt lgkmcnt(0)
	v_pk_add_f32 v[192:193], v[204:205], v[192:193]
	v_pk_add_f32 v[172:173], v[212:213], v[172:173]
	v_exp_f32_e32 v210, v192
	v_exp_f32_e32 v206, v172
	v_exp_f32_e32 v182, v173
	v_exp_f32_e32 v188, v193
	v_exp_f32_e32 v213, v190
	v_pk_add_f32 v[172:173], v[206:207], 0 op_sel_hi:[1,0]
	v_exp_f32_e32 v212, v174
	v_pk_add_f32 v[172:173], v[182:183], v[172:173]
	v_exp_f32_e32 v190, v175
	v_pk_add_f32 v[172:173], v[208:209], v[172:173]
	ds_read_b128 v[192:195], v171 offset:31232
	v_pk_add_f32 v[172:173], v[184:185], v[172:173]
	s_nop 0
	v_pk_add_f32 v[172:173], v[210:211], v[172:173]
	s_nop 0
	v_pk_add_f32 v[172:173], v[188:189], v[172:173]
	s_nop 0
	v_pk_add_f32 v[172:173], v[212:213], v[172:173]
	s_nop 0
	v_pk_add_f32 v[204:205], v[190:191], v[172:173]
	ds_read_b128 v[172:175], v171 offset:28672
	v_cvt_pk_bf16_f32 v200, v207, v183
	v_cvt_pk_bf16_f32 v201, v209, v185
	v_cvt_pk_bf16_f32 v202, v211, v189
	v_cvt_pk_bf16_f32 v203, v213, v191
	s_nop 0
	v_mfma_f32_16x16x32_bf16 v[124:127], v[132:135], v[200:203], v[124:127]
	v_add_f32_e64 v150, v150, v204
	v_add_f32_e64 v151, v151, v205
	v_cvt_pk_bf16_f32 v204, v206, v182
	v_cvt_pk_bf16_f32 v205, v208, v184
	v_mfma_f32_16x16x32_bf16 v[120:123], v[136:139], v[200:203], v[120:123]
	v_cvt_pk_bf16_f32 v206, v210, v188
	v_cvt_pk_bf16_f32 v207, v212, v190
	v_mfma_f32_16x16x32_bf16 v[116:119], v[140:143], v[200:203], v[116:119]
	v_mfma_f32_16x16x32_bf16 v[112:115], v[144:147], v[200:203], v[112:115]
	s_waitcnt lgkmcnt(0)
	s_mul_i32 s69, s58, 0x9800
	v_add3_u32 v239, s69, v165, v167
	ds_read_b128 v[228:231], v239
	ds_read_b128 v[232:235], v239 offset:4608
	ds_read_b128 v[240:243], v239 offset:64
	ds_read_b128 v[244:247], v239 offset:4672
	ds_read_b128 v[248:251], v239 offset:128
	v_mfma_f32_16x16x32_bf16 v[108:111], v[172:175], v[200:203], v[108:111]
	v_mfma_f32_16x16x32_bf16 v[72:75], v[192:195], v[200:203], v[72:75]
	v_mfma_f32_16x16x32_bf16 v[68:71], v[196:199], v[200:203], v[68:71]
	v_mfma_f32_16x16x32_bf16 v[64:67], v[128:131], v[200:203], v[64:67]
	v_mfma_f32_16x16x32_bf16 v[28:31], v[132:135], v[204:207], v[28:31]
	v_mfma_f32_16x16x32_bf16 v[24:27], v[136:139], v[204:207], v[24:27]
	v_mfma_f32_16x16x32_bf16 v[20:23], v[140:143], v[204:207], v[20:23]
	v_mfma_f32_16x16x32_bf16 v[16:19], v[144:147], v[204:207], v[16:19]
	v_mfma_f32_16x16x32_bf16 v[12:15], v[172:175], v[204:207], v[12:15]
	v_mfma_f32_16x16x32_bf16 v[8:11], v[192:195], v[204:207], v[8:11]
	v_mfma_f32_16x16x32_bf16 v[4:7], v[196:199], v[204:207], v[4:7]
	v_mfma_f32_16x16x32_bf16 v[0:3], v[128:131], v[204:207], v[0:3]
	s_mov_b64 s[68:69], 0x100
	v_lshl_add_u64 v[158:159], v[158:159], 0, s[68:69]
	s_mov_b64 s[68:69], 0x180000
	s_add_i32 s41, s41, 2
	v_lshl_add_u64 v[160:161], v[160:161], 0, s[68:69]
	v_add_u32_e32 v170, 0x200, v170
	s_cmp_ge_u32 s59, s40
	s_mov_b32 s63, s58
	s_barrier
	s_cbranch_scc1 .LBB0_128

;     ...
;     auto compute = [&](int buf, int t) {
;         const LAS bf16* Ks = (const LAS bf16*)(lds + koff(buf)); const LAS bf16* VT = (const LAS bf16*)(lds + voff(buf));
;         bf16x8 kf[2][4]; float bias[2][2][4];
; #pragma unroll
;         for (int kb = 0; kb < 2; ++kb)
; #pragma unroll
;             for (int ks = 0; ks < 4; ++ks) kf[kb][ks] = *(const LAS bf16x8*)(Ks + (32 * kh + 16 * kb + fr) * QP + 32 * ks + 8 * fq);
;         if (MODE == 0) { const LAS float* bp = BT + (2047 - 16 - (q0 + 32 * rp + fr - t * 64 - 32 * kh - 4 * fq));
; #pragma unroll
;                 for (int kb = 0; kb < 2; ++kb)
; #pragma unroll
;                     for (int i = 0; i < 4; ++i) bias[0][kb][i] = bp[16 * (kb + 1) + i]; }
;         __builtin_amdgcn_sched_barrier(0);
;         f32x4 s[2][2];
; #pragma unroll
;         for (int rb = 0; rb < 2; ++rb)
; #pragma unroll
;             for (int kb = 0; kb < 2; ++kb) s[rb][kb] = (f32x4){0.f, 0.f, 0.f, 0.f};
;         bf16x8 pf[2];
;         auto smax = [&](int rb) {
;             if (MODE == 0) { s[rb][0] = s[rb][0] + (f32x4){bias[rb][0][0], bias[rb][0][1], bias[rb][0][2], bias[rb][0][3]}; s[rb][1] = s[rb][1] + (f32x4){bias[rb][1][0], bias[rb][1][1], bias[rb][1][2], bias[rb][1][3]}; }
;             else { s[rb][0] = s[rb][0] - bref; s[rb][1] = s[rb][1] - bref; }
;             float ps = 0.f;
; #pragma unroll
;             for (int kb = 0; kb < 2; ++kb)
; #pragma unroll
;                 for (int i = 0; i < 4; ++i) { s[rb][kb][i] = __builtin_amdgcn_exp2f(s[rb][kb][i]); ps += s[rb][kb][i]; }
;             lrun[rb] += ps;
;             u32x4 pw; pw.x = pk2(s[rb][0][0], s[rb][0][1]); pw.y = pk2(s[rb][0][2], s[rb][0][3]); pw.z = pk2(s[rb][1][0], s[rb][1][1]); pw.w = pk2(s[rb][1][2], s[rb][1][3]);
;             pf[rb] = __builtin_bit_cast(bf16x8, pw); };
; #pragma unroll
;         for (int ks = 0; ks < 4; ++ks)
; #pragma unroll
;             for (int kb = 0; kb < 2; ++kb) MMA16(kf[kb][ks], qf[0][ks], s[0][kb]);
;         __builtin_amdgcn_sched_barrier(0);
;         bf16x8 vf[8];
; #pragma unroll
;         for (int db = 0; db < 8; ++db) vf[db] = *(const LAS bf16x8*)(VT + (16 * db + fr) * VPA + 32 * kh + 8 * fq);
;         if (MODE == 0) { const LAS float* bp = BT + (2047 - 16 - (q0 + 32 * rp + fr - t * 64 - 32 * kh - 4 * fq));
; #pragma unroll
;             for (int kb = 0; kb < 2; ++kb)
; #pragma unroll
.LBB0_125:
	s_mul_i32 s78, s63, 0x9800
	s_add_i32 s79, s78, 0
	v_add_u32_e32 v171, s79, v165
	v_add_u32_e32 v182, v171, v167
	ds_read_b128 v[140:143], v182 offset:192
	ds_read_b128 v[192:195], v182 offset:4736
	ds_read_b128 v[196:199], v182 offset:4800
	ds_read2_b32 v[182:183], v170 offset0:16 offset1:17
	ds_read2_b32 v[184:185], v170 offset0:18 offset1:19
	ds_read2_b32 v[188:189], v170 offset0:32 offset1:33
	ds_read2_b32 v[190:191], v170 offset0:34 offset1:35
	s_waitcnt lgkmcnt(7)
	v_mfma_f32_16x16x32_bf16 v[200:203], v[228:231], v[76:79], 0
	v_mfma_f32_16x16x32_bf16 v[204:207], v[232:235], v[76:79], 0
	v_mfma_f32_16x16x32_bf16 v[200:203], v[240:243], v[80:83], v[200:203]
	v_mfma_f32_16x16x32_bf16 v[204:207], v[244:247], v[80:83], v[204:207]
	v_mfma_f32_16x16x32_bf16 v[200:203], v[248:251], v[84:87], v[200:203]
	s_waitcnt lgkmcnt(5)
	v_mfma_f32_16x16x32_bf16 v[204:207], v[192:195], v[84:87], v[204:207]
	v_mfma_f32_16x16x32_bf16 v[200:203], v[140:143], v[88:91], v[200:203]
	s_waitcnt lgkmcnt(4)
	v_mfma_f32_16x16x32_bf16 v[204:207], v[196:199], v[88:91], v[204:207]
	v_mfma_f32_16x16x32_bf16 v[128:131], v[228:231], v[92:95], 0
	ds_read2_b32 v[212:213], v170 offset1:1
	v_add3_u32 v171, v171, v168, v169
	s_waitcnt lgkmcnt(3)
	s_nop 1
	v_pk_add_f32 v[184:185], v[184:185], v[202:203]
	v_pk_add_f32 v[182:183], v[182:183], v[200:201]
	s_waitcnt lgkmcnt(1)
	v_pk_add_f32 v[190:191], v[190:191], v[206:207]
	v_mfma_f32_16x16x32_bf16 v[144:147], v[232:235], v[92:95], 0
	ds_read_b128 v[200:203], v171 offset:36352
	v_pk_add_f32 v[188:189], v[188:189], v[204:205]
	ds_read2_b32 v[224:225], v170 offset0:16 offset1:17
	v_mfma_f32_16x16x32_bf16 v[128:131], v[240:243], v[96:99], v[128:131]
	ds_read_b128 v[204:207], v171 offset:18432
	ds_read2_b32 v[226:227], v170 offset0:18 offset1:19
	ds_read_b128 v[216:219], v171 offset:33792
	v_mfma_f32_16x16x32_bf16 v[132:135], v[244:247], v[96:99], v[144:147]
	s_nop 2
	ds_read_b128 v[144:147], v171 offset:20992
	v_mfma_f32_16x16x32_bf16 v[128:131], v[248:251], v[100:103], v[128:131]
	ds_read_b128 v[172:175], v171 offset:23552
	v_exp_f32_e32 v139, v184
	v_exp_f32_e32 v137, v185
	v_mfma_f32_16x16x32_bf16 v[132:135], v[192:195], v[100:103], v[132:135]
	ds_read_b128 v[192:195], v171 offset:26112
	v_mfma_f32_16x16x32_bf16 v[128:131], v[140:143], v[104:107], v[128:131]
	ds_read_b128 v[208:211], v171 offset:28672
	v_exp_f32_e32 v143, v182
	v_exp_f32_e32 v141, v183
	s_waitcnt lgkmcnt(9)
	s_nop 3
	v_pk_add_f32 v[220:221], v[212:213], v[128:129]
	v_mfma_f32_16x16x32_bf16 v[196:199], v[196:199], v[104:107], v[132:135]
	ds_read2_b32 v[128:129], v170 offset0:2 offset1:3
	ds_read_b128 v[212:215], v171 offset:31232
	v_exp_f32_e32 v142, v220
	v_exp_f32_e32 v135, v188
	v_exp_f32_e32 v133, v189
	s_waitcnt lgkmcnt(1)
	v_pk_add_f32 v[222:223], v[128:129], v[130:131]
	s_nop 0
	v_pk_add_f32 v[182:183], v[226:227], v[198:199]
	v_pk_add_f32 v[184:185], v[224:225], v[196:197]
	v_exp_f32_e32 v131, v190
	v_exp_f32_e32 v129, v191
	v_exp_f32_e32 v140, v221
	v_exp_f32_e32 v138, v222
	v_exp_f32_e32 v136, v223
	v_exp_f32_e32 v134, v184
	v_exp_f32_e32 v132, v185
	v_exp_f32_e32 v130, v182
	v_exp_f32_e32 v128, v183
	v_cvt_pk_bf16_f32 v196, v143, v141
	v_cvt_pk_bf16_f32 v197, v139, v137
	v_cvt_pk_bf16_f32 v198, v135, v133
	v_cvt_pk_bf16_f32 v199, v131, v129
	s_nop 0
	v_mfma_f32_16x16x32_bf16 v[124:127], v[204:207], v[196:199], v[124:127]
	v_mfma_f32_16x16x32_bf16 v[120:123], v[144:147], v[196:199], v[120:123]
	v_mfma_f32_16x16x32_bf16 v[116:119], v[172:175], v[196:199], v[116:119]
	v_mfma_f32_16x16x32_bf16 v[112:115], v[192:195], v[196:199], v[112:115]
	v_mfma_f32_16x16x32_bf16 v[108:111], v[208:211], v[196:199], v[108:111]
	s_waitcnt lgkmcnt(0)
	s_add_i32 s69, s78, 0x9800
	s_cmp_lt_i32 s63, 2
	s_cselect_b32 s69, s69, 0
	v_add3_u32 v239, s69, v165, v167
	ds_read_b128 v[228:231], v239
	ds_read_b128 v[232:235], v239 offset:4608
	ds_read_b128 v[240:243], v239 offset:64
	ds_read_b128 v[244:247], v239 offset:4672
	ds_read_b128 v[248:251], v239 offset:128
	v_mfma_f32_16x16x32_bf16 v[72:75], v[212:215], v[196:199], v[72:75]
	v_mfma_f32_16x16x32_bf16 v[68:71], v[216:219], v[196:199], v[68:71]
	v_mfma_f32_16x16x32_bf16 v[64:67], v[200:203], v[196:199], v[64:67]
	v_cvt_pk_bf16_f32 v196, v142, v140
	v_cvt_pk_bf16_f32 v197, v138, v136
	v_cvt_pk_bf16_f32 v198, v134, v132
	v_cvt_pk_bf16_f32 v199, v130, v128
	s_nop 0
	v_mfma_f32_16x16x32_bf16 v[28:31], v[204:207], v[196:199], v[28:31]
	v_mfma_f32_16x16x32_bf16 v[24:27], v[144:147], v[196:199], v[24:27]
	v_mfma_f32_16x16x32_bf16 v[20:23], v[172:175], v[196:199], v[20:23]
	v_mfma_f32_16x16x32_bf16 v[16:19], v[192:195], v[196:199], v[16:19]
	v_mfma_f32_16x16x32_bf16 v[12:15], v[208:211], v[196:199], v[12:15]
	v_mfma_f32_16x16x32_bf16 v[8:11], v[212:215], v[196:199], v[8:11]
	v_mfma_f32_16x16x32_bf16 v[4:7], v[216:219], v[196:199], v[4:7]
	v_mfma_f32_16x16x32_bf16 v[0:3], v[200:203], v[196:199], v[0:3]
	s_add_i32 s68, s41, -2
	s_cmp_ge_u32 s68, s40
	s_barrier
	s_cbranch_scc1 .LBB0_121
	v_add3_u32 v144, s79, v149, v152
	s_add_i32 s68, s41, -1
	s_cmp_ge_u32 s68, s40
	s_cbranch_scc1 .Lattn_b_short
	s_waitcnt vmcnt(7)
	ds_write_b128 v144, v[48:51]
	s_waitcnt vmcnt(6)
	ds_write_b128 v144, v[52:55] offset:128
	v_add3_u32 v144, s79, v157, v148
	s_waitcnt vmcnt(4)
	s_branch .Lattn_b_join
